# v26 + residual-epilogue stores nontemporal
# baseline (speedup 1.0000x reference)
;     DI void operator()(const f32x4 (&acc)[2][2][4][2], const Unit& u, int wr, int wc, int fr, int fq) const {
;     ...
;         const float* gp = gate + (size_t)bi * MODW + col0;
;         f32x4 gv[2][2];
; #pragma unroll
;         for (int bj = 0; bj < 2; ++bj)
; #pragma unroll
;             for (int n = 0; n < 2; ++n) gv[bj][n] = *(const f32x4*)(gp + bj * HALF + 4 * n) * coef;
; #pragma unroll
;         for (int ai = 0; ai < 2; ++ai)
; #pragma unroll
;             for (int mp = 0; mp < 2; ++mp) {
;                 f32x4 sv[2][2][2];
; #pragma unroll
;                 for (int m = 0; m < 2; ++m)
; #pragma unroll
;                     for (int bj = 0; bj < 2; ++bj)
; #pragma unroll
;                         for (int n = 0; n < 2; ++n) sv[m][bj][n] = *(const f32x4*)(src + (size_t)(rloc + ai * HALF + (2 * mp + m) * 16) * DM + col0 + bj * HALF + 4 * n);
; #pragma unroll
;                 for (int m = 0; m < 2; ++m)
; #pragma unroll
;                     for (int bj = 0; bj < 2; ++bj)
; #pragma unroll
;                         for (int n = 0; n < 2; ++n) *(f32x4*)(dst + (size_t)(rloc + ai * HALF + (2 * mp + m) * 16) * DM + col0 + bj * HALF + 4 * n) = sv[m][bj][n] + gv[bj][n] * acc[ai][bj][2 * mp + m][n];
.LBB0_498:
	s_lshl_b32 s22, s22, 8
	s_add_i32 s33, s22, 0xffff0000
	s_and_b64 s[30:31], exec, s[88:89]
	s_cselect_b32 s22, s33, s22
	v_lshl_or_b32 v184, s26, 8, v170
	s_lshl_b64 s[30:31], s[90:91], 2
	s_add_u32 s30, s68, s30
	s_addc_u32 s31, s69, s31
	v_lshlrev_b32_e32 v184, 2, v184
	v_add_u32_e32 v160, s22, v165
	s_nop 0
	global_load_dwordx4 v[140:143], v184, s[30:31]
	global_load_dwordx4 v[144:147], v184, s[30:31] offset:16
	global_load_dwordx4 v[148:151], v184, s[30:31] offset:512
	global_load_dwordx4 v[152:155], v184, s[30:31] offset:528
	v_lshl_add_u32 v160, v160, 12, v184
	v_add_u32_e32 v161, 0x10000, v160
	v_add_u32_e32 v166, 0x20000, v160
	v_add_u32_e32 v167, 0x30000, v160
	v_add_u32_e32 v156, 0x80000, v160
	v_add_u32_e32 v157, 0x90000, v160
	v_add_u32_e32 v158, 0xa0000, v160
	v_add_u32_e32 v159, 0xb0000, v160
	global_load_dwordx4 v[196:199], v160, s[86:87]
	global_load_dwordx4 v[200:203], v160, s[86:87] offset:16
	global_load_dwordx4 v[204:207], v160, s[86:87] offset:512
	global_load_dwordx4 v[208:211], v160, s[86:87] offset:528
	global_load_dwordx4 v[212:215], v161, s[86:87]
	global_load_dwordx4 v[216:219], v161, s[86:87] offset:16
	global_load_dwordx4 v[220:223], v161, s[86:87] offset:512
	global_load_dwordx4 v[224:227], v161, s[86:87] offset:528
	global_load_dwordx4 v[228:231], v166, s[86:87]
	global_load_dwordx4 v[232:235], v166, s[86:87] offset:16
	global_load_dwordx4 v[236:239], v166, s[86:87] offset:512
	global_load_dwordx4 v[240:243], v166, s[86:87] offset:528
	global_load_dwordx4 v[244:247], v167, s[86:87]
	global_load_dwordx4 v[248:251], v167, s[86:87] offset:16
	global_load_dwordx4 v[172:175], v167, s[86:87] offset:512
	global_load_dwordx4 v[176:179], v167, s[86:87] offset:528
	s_waitcnt vmcnt(16)
	v_pk_mul_f32 v[140:141], s[70:71], v[140:141]
	v_pk_mul_f32 v[142:143], s[78:79], v[142:143]
	v_pk_mul_f32 v[144:145], s[70:71], v[144:145]
	v_pk_mul_f32 v[146:147], s[78:79], v[146:147]
	v_pk_mul_f32 v[148:149], s[70:71], v[148:149]
	v_pk_mul_f32 v[150:151], s[78:79], v[150:151]
	v_pk_mul_f32 v[152:153], s[70:71], v[152:153]
	v_pk_mul_f32 v[154:155], s[78:79], v[154:155]
	s_waitcnt vmcnt(0)
	v_pk_fma_f32 v[126:127], v[126:127], v[140:141], v[196:197]
	v_pk_fma_f32 v[128:129], v[128:129], v[142:143], v[198:199]
	v_pk_fma_f32 v[122:123], v[122:123], v[144:145], v[200:201]
	v_pk_fma_f32 v[124:125], v[124:125], v[146:147], v[202:203]
	v_pk_fma_f32 v[110:111], v[110:111], v[148:149], v[204:205]
	v_pk_fma_f32 v[112:113], v[112:113], v[150:151], v[206:207]
	v_pk_fma_f32 v[106:107], v[106:107], v[152:153], v[208:209]
	v_pk_fma_f32 v[108:109], v[108:109], v[154:155], v[210:211]
	v_pk_fma_f32 v[118:119], v[118:119], v[140:141], v[212:213]
	v_pk_fma_f32 v[120:121], v[120:121], v[142:143], v[214:215]
	v_pk_fma_f32 v[114:115], v[114:115], v[144:145], v[216:217]
	v_pk_fma_f32 v[116:117], v[116:117], v[146:147], v[218:219]
	v_pk_fma_f32 v[102:103], v[102:103], v[148:149], v[220:221]
	v_pk_fma_f32 v[104:105], v[104:105], v[150:151], v[222:223]
	v_pk_fma_f32 v[98:99], v[98:99], v[152:153], v[224:225]
	v_pk_fma_f32 v[100:101], v[100:101], v[154:155], v[226:227]
	v_pk_fma_f32 v[94:95], v[94:95], v[140:141], v[228:229]
	v_pk_fma_f32 v[96:97], v[96:97], v[142:143], v[230:231]
	v_pk_fma_f32 v[90:91], v[90:91], v[144:145], v[232:233]
	v_pk_fma_f32 v[92:93], v[92:93], v[146:147], v[234:235]
	v_pk_fma_f32 v[78:79], v[78:79], v[148:149], v[236:237]
	v_pk_fma_f32 v[80:81], v[80:81], v[150:151], v[238:239]
	v_pk_fma_f32 v[74:75], v[74:75], v[152:153], v[240:241]
	v_pk_fma_f32 v[76:77], v[76:77], v[154:155], v[242:243]
	v_pk_fma_f32 v[86:87], v[86:87], v[140:141], v[244:245]
	v_pk_fma_f32 v[88:89], v[88:89], v[142:143], v[246:247]
	v_pk_fma_f32 v[82:83], v[82:83], v[144:145], v[248:249]
	v_pk_fma_f32 v[84:85], v[84:85], v[146:147], v[250:251]
	v_pk_fma_f32 v[70:71], v[70:71], v[148:149], v[172:173]
	v_pk_fma_f32 v[72:73], v[72:73], v[150:151], v[174:175]
	v_pk_fma_f32 v[66:67], v[66:67], v[152:153], v[176:177]
	v_pk_fma_f32 v[68:69], v[68:69], v[154:155], v[178:179]
	global_load_dwordx4 v[196:199], v156, s[86:87]
	global_load_dwordx4 v[200:203], v156, s[86:87] offset:16
	global_load_dwordx4 v[204:207], v156, s[86:87] offset:512
	global_load_dwordx4 v[208:211], v156, s[86:87] offset:528
	global_load_dwordx4 v[212:215], v157, s[86:87]
	global_load_dwordx4 v[216:219], v157, s[86:87] offset:16
	global_load_dwordx4 v[220:223], v157, s[86:87] offset:512
	global_load_dwordx4 v[224:227], v157, s[86:87] offset:528
	global_load_dwordx4 v[228:231], v158, s[86:87]
	global_load_dwordx4 v[232:235], v158, s[86:87] offset:16
	global_load_dwordx4 v[236:239], v158, s[86:87] offset:512
	global_load_dwordx4 v[240:243], v158, s[86:87] offset:528
	global_load_dwordx4 v[244:247], v159, s[86:87]
	global_load_dwordx4 v[248:251], v159, s[86:87] offset:16
	global_load_dwordx4 v[172:175], v159, s[86:87] offset:512
	global_load_dwordx4 v[176:179], v159, s[86:87] offset:528
	global_store_dwordx4 v160, v[126:129], s[84:85] nt
	global_store_dwordx4 v160, v[122:125], s[84:85] offset:16 nt
	global_store_dwordx4 v160, v[110:113], s[84:85] offset:512 nt
	global_store_dwordx4 v160, v[106:109], s[84:85] offset:528 nt
	global_store_dwordx4 v161, v[118:121], s[84:85] nt
	global_store_dwordx4 v161, v[114:117], s[84:85] offset:16 nt
	global_store_dwordx4 v161, v[102:105], s[84:85] offset:512 nt
	global_store_dwordx4 v161, v[98:101], s[84:85] offset:528 nt
	global_store_dwordx4 v166, v[94:97], s[84:85] nt
	global_store_dwordx4 v166, v[90:93], s[84:85] offset:16 nt
	global_store_dwordx4 v166, v[78:81], s[84:85] offset:512 nt
	global_store_dwordx4 v166, v[74:77], s[84:85] offset:528 nt
	global_store_dwordx4 v167, v[86:89], s[84:85] nt
	global_store_dwordx4 v167, v[82:85], s[84:85] offset:16 nt
	global_store_dwordx4 v167, v[70:73], s[84:85] offset:512 nt
	global_store_dwordx4 v167, v[66:69], s[84:85] offset:528 nt
	s_waitcnt vmcnt(16)
; #define PG8_BAR __builtin_amdgcn_s_barrier()
; template <class Epi>
; DI void gemm_phase(LAS unsigned char* lds, int tid, const Gemm g, const Order& S, const Epi& E) {
;     ...
;         if (!has_next) break;
; #pragma unroll
;         for (int a = 0; a < 2; ++a)
; #pragma unroll
;             for (int b = 0; b < 2; ++b)
; #pragma unroll
;                 for (int m = 0; m < 4; ++m)
; #pragma unroll
;                     for (int n = 0; n < 2; ++n) acc[a][b][m][n] = (f32x4){0.f, 0.f, 0.f, 0.f};
;         cur = nxt; cA = nA; cB = nB; ++ui;
;         if (wr == 1) PG8_BAR;
;     DI void operator()(const f32x4 (&acc)[2][2][4][2], const Unit& u, int wr, int wc, int fr, int fq) const {
;     ...
;                 for (int m = 0; m < 2; ++m)
; #pragma unroll
;                     for (int bj = 0; bj < 2; ++bj)
; #pragma unroll
;                         for (int n = 0; n < 2; ++n) *(f32x4*)(dst + (size_t)(rloc + ai * HALF + (2 * mp + m) * 16) * DM + col0 + bj * HALF + 4 * n) = sv[m][bj][n] + gv[bj][n] * acc[ai][bj][2 * mp + m][n];
	v_pk_fma_f32 v[62:63], v[62:63], v[140:141], v[196:197]
	v_pk_fma_f32 v[64:65], v[64:65], v[142:143], v[198:199]
	v_pk_fma_f32 v[58:59], v[58:59], v[144:145], v[200:201]
	v_pk_fma_f32 v[60:61], v[60:61], v[146:147], v[202:203]
	v_pk_fma_f32 v[46:47], v[46:47], v[148:149], v[204:205]
	v_pk_fma_f32 v[48:49], v[48:49], v[150:151], v[206:207]
	v_pk_fma_f32 v[42:43], v[42:43], v[152:153], v[208:209]
	v_pk_fma_f32 v[44:45], v[44:45], v[154:155], v[210:211]
	v_pk_fma_f32 v[54:55], v[54:55], v[140:141], v[212:213]
	v_pk_fma_f32 v[56:57], v[56:57], v[142:143], v[214:215]
	v_pk_fma_f32 v[50:51], v[50:51], v[144:145], v[216:217]
	v_pk_fma_f32 v[52:53], v[52:53], v[146:147], v[218:219]
	v_pk_fma_f32 v[38:39], v[38:39], v[148:149], v[220:221]
	v_pk_fma_f32 v[40:41], v[40:41], v[150:151], v[222:223]
	v_pk_fma_f32 v[34:35], v[34:35], v[152:153], v[224:225]
	v_pk_fma_f32 v[36:37], v[36:37], v[154:155], v[226:227]
	v_pk_fma_f32 v[30:31], v[30:31], v[140:141], v[228:229]
	v_pk_fma_f32 v[32:33], v[32:33], v[142:143], v[230:231]
	v_pk_fma_f32 v[26:27], v[26:27], v[144:145], v[232:233]
	v_pk_fma_f32 v[28:29], v[28:29], v[146:147], v[234:235]
	v_pk_fma_f32 v[14:15], v[14:15], v[148:149], v[236:237]
	v_pk_fma_f32 v[16:17], v[16:17], v[150:151], v[238:239]
	v_pk_fma_f32 v[10:11], v[10:11], v[152:153], v[240:241]
	v_pk_fma_f32 v[12:13], v[12:13], v[154:155], v[242:243]
	v_pk_fma_f32 v[22:23], v[22:23], v[140:141], v[244:245]
	v_pk_fma_f32 v[24:25], v[24:25], v[142:143], v[246:247]
	v_pk_fma_f32 v[18:19], v[18:19], v[144:145], v[248:249]
	v_pk_fma_f32 v[20:21], v[20:21], v[146:147], v[250:251]
	v_pk_fma_f32 v[6:7], v[6:7], v[148:149], v[172:173]
	v_pk_fma_f32 v[8:9], v[8:9], v[150:151], v[174:175]
	v_pk_fma_f32 v[2:3], v[2:3], v[152:153], v[176:177]
	v_pk_fma_f32 v[4:5], v[4:5], v[154:155], v[178:179]
	global_store_dwordx4 v156, v[62:65], s[84:85] nt
	global_store_dwordx4 v156, v[58:61], s[84:85] offset:16 nt
	global_store_dwordx4 v156, v[46:49], s[84:85] offset:512 nt
	global_store_dwordx4 v156, v[42:45], s[84:85] offset:528 nt
	global_store_dwordx4 v157, v[54:57], s[84:85] nt
	global_store_dwordx4 v157, v[50:53], s[84:85] offset:16 nt
	global_store_dwordx4 v157, v[38:41], s[84:85] offset:512 nt
	global_store_dwordx4 v157, v[34:37], s[84:85] offset:528 nt
	global_store_dwordx4 v158, v[30:33], s[84:85] nt
	global_store_dwordx4 v158, v[26:29], s[84:85] offset:16 nt
	global_store_dwordx4 v158, v[14:17], s[84:85] offset:512 nt
	global_store_dwordx4 v158, v[10:13], s[84:85] offset:528 nt
	global_store_dwordx4 v159, v[22:25], s[84:85] nt
	global_store_dwordx4 v159, v[18:21], s[84:85] offset:16 nt
	global_store_dwordx4 v159, v[6:9], s[84:85] offset:512 nt
	global_store_dwordx4 v159, v[2:5], s[84:85] offset:528 nt
	s_mov_b64 s[84:85], -1
	s_and_b64 vcc, exec, s[4:5]
	s_cbranch_vccnz .LBB0_485
	s_andn2_b64 vcc, exec, s[76:77]
	s_cbranch_vccnz .LBB0_484
	s_barrier
	s_branch .LBB0_484
